# phase 3 item body re-written: partial loads hoisted, rcp-form gelu, f32-operand MFMA for the 256x64 product, 4 rows finalised together
# speedup vs baseline: 1.0314x; 1.0006x over previous
; #define LAS __attribute__((address_space(3)))
; __device__ __forceinline__ void phase3(const Args& a, LAS unsigned char* lds) {
;     ...
;     for (int item = blockIdx.x; item < nchunk; item += gridDim.x) {
;         const int kv = (item * 32) >> 12;
;         __syncthreads();
;         { const f32x4* src = (const f32x4*)(a.in[7] + (size_t)kv * 256 * 64);
; #pragma unroll
;           for (int i = 0; i < 8; ++i) ((LAS f32x4*)w2s)[tid + 512 * i] = src[tid + 512 * i]; }
;         if (tid < 256) { float t = 0.f;
; #pragma unroll
;             for (int kch = 0; kch < 64; ++kch) t += c1p[kch * 512 + kv * 256 + tid];
;             c1s[tid] = t; }
;         __syncthreads();
; #pragma unroll 1
;         for (int rr = 0; rr < 4; ++rr) {
;             const int R = item * 32 + wave * 4 + rr, bh = (R >> 7) & 31, n = R & 127;
;             f32x4 h4 = *(const LAS f32x4*)(c1s + 4 * lane);
; #pragma unroll
;             for (int kc = 0; kc < 4; ++kc) h4 += *(const f32x4*)(part + ((size_t)kc * 8192 + R) * 256 + 4 * lane);
.LBB0_589:
	s_ashr_i32 s4, s20, 7
	s_ashr_i32 s5, s4, 31
	s_lshl_b64 s[0:1], s[4:5], 16
	s_add_u32 s0, s86, s0
	s_addc_u32 s1, s87, s1
	v_lshl_add_u64 v[10:11], s[0:1], 0, v[8:9]
	v_add_co_u32_e32 v36, vcc, s14, v10
	s_waitcnt vmcnt(0) lgkmcnt(0)
	s_nop 0
	v_addc_co_u32_e32 v37, vcc, 0, v11, vcc
	v_add_co_u32_e32 v44, vcc, s15, v10
	s_barrier
	v_lshl_add_u32 v168, s20, 5, v13
	v_mov_b32_e32 v169, 0
	v_lshlrev_b64 v[168:169], 10, v[168:169]
	v_lshl_add_u64 v[168:169], v[4:5], 0, v[168:169]
	s_mov_b32 s6, 0x800000
	s_mov_b32 s7, 0
	v_lshl_add_u64 v[170:171], v[168:169], 0, s[6:7]
	v_lshl_add_u64 v[172:173], v[170:171], 0, s[6:7]
	v_lshl_add_u64 v[174:175], v[172:173], 0, s[6:7]
	global_load_dwordx4 v[100:103], v[168:169], off
	global_load_dwordx4 v[104:107], v[170:171], off
	global_load_dwordx4 v[108:111], v[172:173], off
	global_load_dwordx4 v[112:115], v[174:175], off
	global_load_dwordx4 v[116:119], v[168:169], off offset:1024
	global_load_dwordx4 v[120:123], v[170:171], off offset:1024
	global_load_dwordx4 v[124:127], v[172:173], off offset:1024
	global_load_dwordx4 v[128:131], v[174:175], off offset:1024
	global_load_dwordx4 v[132:135], v[168:169], off offset:2048
	global_load_dwordx4 v[136:139], v[170:171], off offset:2048
	global_load_dwordx4 v[140:143], v[172:173], off offset:2048
	global_load_dwordx4 v[144:147], v[174:175], off offset:2048
	global_load_dwordx4 v[152:155], v[168:169], off offset:3072
	global_load_dwordx4 v[156:159], v[170:171], off offset:3072
	global_load_dwordx4 v[160:163], v[172:173], off offset:3072
	global_load_dwordx4 v[164:167], v[174:175], off offset:3072
	global_load_dword v176, v[6:7], off
	s_nop 0
	v_addc_co_u32_e32 v45, vcc, 0, v11, vcc
	v_add_co_u32_e32 v52, vcc, 0xa000, v10
	s_nop 1
	v_addc_co_u32_e32 v53, vcc, 0, v11, vcc
	global_load_dwordx4 v[24:27], v8, s[0:1]
	global_load_dwordx4 v[28:31], v[36:37], off
	global_load_dwordx4 v[32:35], v1, s[0:1]
	s_nop 0
	global_load_dwordx4 v[36:39], v[44:45], off
	global_load_dwordx4 v[40:43], v19, s[0:1]
	s_nop 0
	global_load_dwordx4 v[44:47], v[52:53], off
	global_load_dwordx4 v[48:51], v20, s[0:1]
	v_add_co_u32_e32 v10, vcc, 0xe000, v10
	s_nop 1
	v_addc_co_u32_e32 v11, vcc, 0, v11, vcc
	global_load_dwordx4 v[52:55], v[10:11], off
	s_waitcnt vmcnt(7)
	ds_write_b128 v18, v[24:27]
	s_waitcnt vmcnt(6)
	ds_write_b128 v18, v[28:31] offset:8192
	s_waitcnt vmcnt(5)
	ds_write_b128 v18, v[32:35] offset:16384
	s_waitcnt vmcnt(4)
	ds_write_b128 v18, v[36:39] offset:24576
	s_waitcnt vmcnt(3)
	ds_write_b128 v18, v[40:43] offset:32768
	s_waitcnt vmcnt(2)
	ds_write_b128 v18, v[44:47] offset:40960
	s_waitcnt vmcnt(1)
	ds_write_b128 v18, v[48:51] offset:49152
	s_waitcnt vmcnt(0)
	ds_write_b128 v18, v[52:55] offset:57344
	s_and_saveexec_b64 s[0:1], s[2:3]
	s_cbranch_execz .LBB0_591
	v_lshl_or_b32 v10, s4, 8, v184
	v_add_u32_e32 v24, 0x200, v10
	v_ashrrev_i32_e32 v25, 31, v24
	v_lshl_add_u64 v[32:33], v[24:25], 2, s[10:11]
	v_add_u32_e32 v24, 0x400, v10
	v_ashrrev_i32_e32 v25, 31, v24
	v_lshl_add_u64 v[34:35], v[24:25], 2, s[10:11]
	v_add_u32_e32 v24, 0x600, v10
	v_ashrrev_i32_e32 v25, 31, v24
	v_lshl_add_u64 v[36:37], v[24:25], 2, s[10:11]
	v_add_u32_e32 v24, 0x800, v10
	v_ashrrev_i32_e32 v25, 31, v24
	v_lshl_add_u64 v[38:39], v[24:25], 2, s[10:11]
	v_add_u32_e32 v24, 0xa00, v10
	v_ashrrev_i32_e32 v25, 31, v24
	v_lshl_add_u64 v[40:41], v[24:25], 2, s[10:11]
	v_add_u32_e32 v24, 0xc00, v10
	v_ashrrev_i32_e32 v25, 31, v24
	v_ashrrev_i32_e32 v11, 31, v10
	v_lshl_add_u64 v[42:43], v[24:25], 2, s[10:11]
	v_add_u32_e32 v24, 0xe00, v10
	v_lshl_add_u64 v[30:31], v[10:11], 2, s[10:11]
	v_ashrrev_i32_e32 v25, 31, v24
	v_lshl_add_u64 v[44:45], v[24:25], 2, s[10:11]
	global_load_dword v2, v[30:31], off
	global_load_dword v11, v[32:33], off
	global_load_dword v23, v[34:35], off
	global_load_dword v24, v[36:37], off
	global_load_dword v25, v[38:39], off
	global_load_dword v26, v[40:41], off
	global_load_dword v27, v[42:43], off
	global_load_dword v28, v[44:45], off
	v_add_u32_e32 v30, 0x1000, v10
	v_ashrrev_i32_e32 v31, 31, v30
	v_add_u32_e32 v32, 0x1200, v10
	v_add_u32_e32 v34, 0x1400, v10
	v_add_u32_e32 v36, 0x1600, v10
	v_add_u32_e32 v38, 0x1800, v10
	v_add_u32_e32 v40, 0x1a00, v10
	v_add_u32_e32 v42, 0x1c00, v10
	v_add_u32_e32 v44, 0x1e00, v10
	v_lshl_add_u64 v[30:31], v[30:31], 2, s[10:11]
	v_ashrrev_i32_e32 v33, 31, v32
	v_ashrrev_i32_e32 v35, 31, v34
	v_ashrrev_i32_e32 v37, 31, v36
	v_ashrrev_i32_e32 v39, 31, v38
	v_ashrrev_i32_e32 v41, 31, v40
	v_ashrrev_i32_e32 v43, 31, v42
	v_ashrrev_i32_e32 v45, 31, v44
	v_lshl_add_u64 v[32:33], v[32:33], 2, s[10:11]
	v_lshl_add_u64 v[34:35], v[34:35], 2, s[10:11]
	v_lshl_add_u64 v[36:37], v[36:37], 2, s[10:11]
	v_lshl_add_u64 v[38:39], v[38:39], 2, s[10:11]
	v_lshl_add_u64 v[40:41], v[40:41], 2, s[10:11]
	v_lshl_add_u64 v[42:43], v[42:43], 2, s[10:11]
	v_lshl_add_u64 v[44:45], v[44:45], 2, s[10:11]
	global_load_dword v29, v[30:31], off
	global_load_dword v46, v[32:33], off
	global_load_dword v47, v[34:35], off
	global_load_dword v48, v[36:37], off
	global_load_dword v49, v[38:39], off
	global_load_dword v50, v[40:41], off
	global_load_dword v51, v[42:43], off
	global_load_dword v52, v[44:45], off
	v_add_u32_e32 v30, 0x2000, v10
	v_ashrrev_i32_e32 v31, 31, v30
	v_add_u32_e32 v32, 0x2200, v10
	v_add_u32_e32 v34, 0x2400, v10
	v_add_u32_e32 v36, 0x2600, v10
	v_add_u32_e32 v38, 0x2800, v10
	v_add_u32_e32 v40, 0x2a00, v10
	v_add_u32_e32 v42, 0x2c00, v10
	v_add_u32_e32 v44, 0x2e00, v10
	v_lshl_add_u64 v[30:31], v[30:31], 2, s[10:11]
	v_ashrrev_i32_e32 v33, 31, v32
	v_ashrrev_i32_e32 v35, 31, v34
	v_ashrrev_i32_e32 v37, 31, v36
	v_ashrrev_i32_e32 v39, 31, v38
; __device__ __forceinline__ void phase3(const Args& a, LAS unsigned char* lds) {
;     ...
;         if (tid < 256) { float t = 0.f;
; #pragma unroll
;             for (int kch = 0; kch < 64; ++kch) t += c1p[kch * 512 + kv * 256 + tid];
;             c1s[tid] = t; }
	v_ashrrev_i32_e32 v41, 31, v40
	v_ashrrev_i32_e32 v43, 31, v42
	v_ashrrev_i32_e32 v45, 31, v44
	v_lshl_add_u64 v[32:33], v[32:33], 2, s[10:11]
	v_lshl_add_u64 v[34:35], v[34:35], 2, s[10:11]
	v_lshl_add_u64 v[36:37], v[36:37], 2, s[10:11]
	v_lshl_add_u64 v[38:39], v[38:39], 2, s[10:11]
	v_lshl_add_u64 v[40:41], v[40:41], 2, s[10:11]
	v_lshl_add_u64 v[42:43], v[42:43], 2, s[10:11]
	v_lshl_add_u64 v[44:45], v[44:45], 2, s[10:11]
	global_load_dword v53, v[30:31], off
	global_load_dword v54, v[32:33], off
	global_load_dword v55, v[34:35], off
	global_load_dword v56, v[36:37], off
	global_load_dword v57, v[38:39], off
	global_load_dword v58, v[40:41], off
	global_load_dword v59, v[42:43], off
	global_load_dword v60, v[44:45], off
	v_add_u32_e32 v30, 0x3000, v10
	v_ashrrev_i32_e32 v31, 31, v30
	v_add_u32_e32 v32, 0x3200, v10
	v_add_u32_e32 v34, 0x3400, v10
	v_add_u32_e32 v36, 0x3600, v10
	v_add_u32_e32 v38, 0x3800, v10
	v_add_u32_e32 v40, 0x3a00, v10
	v_add_u32_e32 v42, 0x3c00, v10
	v_add_u32_e32 v44, 0x3e00, v10
	v_lshl_add_u64 v[30:31], v[30:31], 2, s[10:11]
	v_ashrrev_i32_e32 v33, 31, v32
	v_ashrrev_i32_e32 v35, 31, v34
	v_ashrrev_i32_e32 v37, 31, v36
	v_ashrrev_i32_e32 v39, 31, v38
	v_ashrrev_i32_e32 v41, 31, v40
	v_ashrrev_i32_e32 v43, 31, v42
	v_ashrrev_i32_e32 v45, 31, v44
	v_lshl_add_u64 v[32:33], v[32:33], 2, s[10:11]
	v_lshl_add_u64 v[34:35], v[34:35], 2, s[10:11]
	v_lshl_add_u64 v[36:37], v[36:37], 2, s[10:11]
	v_lshl_add_u64 v[38:39], v[38:39], 2, s[10:11]
	v_lshl_add_u64 v[40:41], v[40:41], 2, s[10:11]
	v_lshl_add_u64 v[42:43], v[42:43], 2, s[10:11]
	v_lshl_add_u64 v[44:45], v[44:45], 2, s[10:11]
	global_load_dword v61, v[30:31], off
	global_load_dword v62, v[32:33], off
	global_load_dword v63, v[34:35], off
	global_load_dword v64, v[36:37], off
	global_load_dword v65, v[38:39], off
	global_load_dword v66, v[40:41], off
	global_load_dword v67, v[42:43], off
	global_load_dword v68, v[44:45], off
	v_add_u32_e32 v30, 0x4000, v10
	v_ashrrev_i32_e32 v31, 31, v30
	v_add_u32_e32 v32, 0x4200, v10
	v_add_u32_e32 v34, 0x4400, v10
	v_add_u32_e32 v36, 0x4600, v10
	v_add_u32_e32 v38, 0x4800, v10
	v_add_u32_e32 v40, 0x4a00, v10
	v_add_u32_e32 v42, 0x4c00, v10
	v_add_u32_e32 v44, 0x4e00, v10
	v_lshl_add_u64 v[30:31], v[30:31], 2, s[10:11]
	v_ashrrev_i32_e32 v33, 31, v32
	v_ashrrev_i32_e32 v35, 31, v34
	v_ashrrev_i32_e32 v37, 31, v36
	v_ashrrev_i32_e32 v39, 31, v38
	v_ashrrev_i32_e32 v41, 31, v40
	v_ashrrev_i32_e32 v43, 31, v42
	v_ashrrev_i32_e32 v45, 31, v44
	v_lshl_add_u64 v[32:33], v[32:33], 2, s[10:11]
	v_lshl_add_u64 v[34:35], v[34:35], 2, s[10:11]
	v_lshl_add_u64 v[36:37], v[36:37], 2, s[10:11]
	v_lshl_add_u64 v[38:39], v[38:39], 2, s[10:11]
	v_lshl_add_u64 v[40:41], v[40:41], 2, s[10:11]
	v_lshl_add_u64 v[42:43], v[42:43], 2, s[10:11]
	v_lshl_add_u64 v[44:45], v[44:45], 2, s[10:11]
	global_load_dword v69, v[30:31], off
	global_load_dword v70, v[32:33], off
	global_load_dword v71, v[34:35], off
	global_load_dword v72, v[36:37], off
	global_load_dword v73, v[38:39], off
	global_load_dword v74, v[40:41], off
	global_load_dword v75, v[42:43], off
	global_load_dword v76, v[44:45], off
	v_add_u32_e32 v30, 0x5000, v10
	v_ashrrev_i32_e32 v31, 31, v30
	v_add_u32_e32 v32, 0x5200, v10
	v_add_u32_e32 v34, 0x5400, v10
	v_add_u32_e32 v36, 0x5600, v10
	v_add_u32_e32 v38, 0x5800, v10
	v_add_u32_e32 v40, 0x5a00, v10
	v_add_u32_e32 v42, 0x5c00, v10
	v_add_u32_e32 v44, 0x5e00, v10
	v_lshl_add_u64 v[30:31], v[30:31], 2, s[10:11]
	v_ashrrev_i32_e32 v33, 31, v32
	v_ashrrev_i32_e32 v35, 31, v34
	v_ashrrev_i32_e32 v37, 31, v36
	v_ashrrev_i32_e32 v39, 31, v38
	v_ashrrev_i32_e32 v41, 31, v40
	v_ashrrev_i32_e32 v43, 31, v42
	v_ashrrev_i32_e32 v45, 31, v44
	v_lshl_add_u64 v[32:33], v[32:33], 2, s[10:11]
	v_lshl_add_u64 v[34:35], v[34:35], 2, s[10:11]
	v_lshl_add_u64 v[36:37], v[36:37], 2, s[10:11]
	v_lshl_add_u64 v[38:39], v[38:39], 2, s[10:11]
	v_lshl_add_u64 v[40:41], v[40:41], 2, s[10:11]
	v_lshl_add_u64 v[42:43], v[42:43], 2, s[10:11]
	v_lshl_add_u64 v[44:45], v[44:45], 2, s[10:11]
	global_load_dword v77, v[30:31], off
	global_load_dword v78, v[32:33], off
	global_load_dword v79, v[34:35], off
	global_load_dword v80, v[36:37], off
	global_load_dword v81, v[38:39], off
	global_load_dword v82, v[40:41], off
	global_load_dword v83, v[42:43], off
	global_load_dword v84, v[44:45], off
	v_add_u32_e32 v30, 0x6000, v10
	v_ashrrev_i32_e32 v31, 31, v30
	v_add_u32_e32 v32, 0x6200, v10
	v_add_u32_e32 v34, 0x6400, v10
	v_add_u32_e32 v36, 0x6600, v10
	v_add_u32_e32 v38, 0x6800, v10
	v_add_u32_e32 v40, 0x6a00, v10
	v_add_u32_e32 v42, 0x6c00, v10
	v_add_u32_e32 v44, 0x6e00, v10
	v_lshl_add_u64 v[30:31], v[30:31], 2, s[10:11]
	v_ashrrev_i32_e32 v33, 31, v32
	v_ashrrev_i32_e32 v35, 31, v34
	v_ashrrev_i32_e32 v37, 31, v36
	v_ashrrev_i32_e32 v39, 31, v38
	v_ashrrev_i32_e32 v41, 31, v40
	v_ashrrev_i32_e32 v43, 31, v42
	v_ashrrev_i32_e32 v45, 31, v44
	v_lshl_add_u64 v[32:33], v[32:33], 2, s[10:11]
	v_lshl_add_u64 v[34:35], v[34:35], 2, s[10:11]
	v_lshl_add_u64 v[36:37], v[36:37], 2, s[10:11]
	v_lshl_add_u64 v[38:39], v[38:39], 2, s[10:11]
	v_lshl_add_u64 v[40:41], v[40:41], 2, s[10:11]
	v_lshl_add_u64 v[42:43], v[42:43], 2, s[10:11]
	v_lshl_add_u64 v[44:45], v[44:45], 2, s[10:11]
	global_load_dword v85, v[30:31], off
	global_load_dword v86, v[32:33], off
	global_load_dword v87, v[34:35], off
	global_load_dword v88, v[36:37], off
	global_load_dword v89, v[38:39], off
	global_load_dword v90, v[40:41], off
	global_load_dword v91, v[42:43], off
	global_load_dword v92, v[44:45], off
	v_add_u32_e32 v30, 0x7000, v10
	v_ashrrev_i32_e32 v31, 31, v30
	v_add_u32_e32 v32, 0x7200, v10
	v_add_u32_e32 v34, 0x7400, v10
	v_add_u32_e32 v36, 0x7600, v10
	v_add_u32_e32 v38, 0x7800, v10
	v_add_u32_e32 v40, 0x7a00, v10
	v_add_u32_e32 v42, 0x7c00, v10
	v_add_u32_e32 v44, 0x7e00, v10
	v_lshl_add_u64 v[30:31], v[30:31], 2, s[10:11]
	v_ashrrev_i32_e32 v33, 31, v32
	v_ashrrev_i32_e32 v35, 31, v34
	v_ashrrev_i32_e32 v37, 31, v36
	v_ashrrev_i32_e32 v39, 31, v38
	v_ashrrev_i32_e32 v41, 31, v40
	v_ashrrev_i32_e32 v43, 31, v42
	v_ashrrev_i32_e32 v45, 31, v44
	v_lshl_add_u64 v[32:33], v[32:33], 2, s[10:11]
	v_lshl_add_u64 v[34:35], v[34:35], 2, s[10:11]
	v_lshl_add_u64 v[36:37], v[36:37], 2, s[10:11]
	v_lshl_add_u64 v[38:39], v[38:39], 2, s[10:11]
	v_lshl_add_u64 v[40:41], v[40:41], 2, s[10:11]
	v_lshl_add_u64 v[42:43], v[42:43], 2, s[10:11]
	v_lshl_add_u64 v[44:45], v[44:45], 2, s[10:11]
	global_load_dword v10, v[30:31], off
	global_load_dword v93, v[32:33], off
	global_load_dword v94, v[34:35], off
	global_load_dword v95, v[36:37], off
	global_load_dword v96, v[38:39], off
	global_load_dword v97, v[40:41], off
	global_load_dword v98, v[42:43], off
	global_load_dword v99, v[44:45], off
	s_waitcnt vmcnt(62)
; #define LAS __attribute__((address_space(3)))
; __device__ __forceinline__ float gelu_tanh(float x) {
;     const float u = 0.7978845608028654f * (x + 0.044715f * x * x * x);
;     return x / (1.f + __expf(-2.f * u));
; }
; __device__ __forceinline__ void phase3(const Args& a, LAS unsigned char* lds) {
;     ...
;         if (tid < 256) { float t = 0.f;
; #pragma unroll
;             for (int kch = 0; kch < 64; ++kch) t += c1p[kch * 512 + kv * 256 + tid];
;             c1s[tid] = t; }
;         __syncthreads();
; #pragma unroll 1
;         for (int rr = 0; rr < 4; ++rr) {
;             const int R = item * 32 + wave * 4 + rr, bh = (R >> 7) & 31, n = R & 127;
;             f32x4 h4 = *(const LAS f32x4*)(c1s + 4 * lane);
; #pragma unroll
;             for (int kc = 0; kc < 4; ++kc) h4 += *(const f32x4*)(part + ((size_t)kc * 8192 + R) * 256 + 4 * lane);
;             h4.x = gelu_tanh(h4.x); h4.y = gelu_tanh(h4.y); h4.z = gelu_tanh(h4.z); h4.w = gelu_tanh(h4.w);
	v_add_f32_e32 v2, 0, v2
	v_add_f32_e32 v2, v2, v11
	s_waitcnt vmcnt(61)
	v_add_f32_e32 v2, v2, v23
	s_waitcnt vmcnt(60)
	v_add_f32_e32 v2, v2, v24
	s_waitcnt vmcnt(59)
	v_add_f32_e32 v2, v2, v25
	s_waitcnt vmcnt(58)
	v_add_f32_e32 v2, v2, v26
	s_waitcnt vmcnt(57)
	v_add_f32_e32 v2, v2, v27
	s_waitcnt vmcnt(56)
	v_add_f32_e32 v2, v2, v28
	s_waitcnt vmcnt(55)
	v_add_f32_e32 v2, v2, v29
	s_waitcnt vmcnt(54)
	v_add_f32_e32 v2, v2, v46
	s_waitcnt vmcnt(53)
	v_add_f32_e32 v2, v2, v47
	s_waitcnt vmcnt(52)
	v_add_f32_e32 v2, v2, v48
	s_waitcnt vmcnt(51)
	v_add_f32_e32 v2, v2, v49
	s_waitcnt vmcnt(50)
	v_add_f32_e32 v2, v2, v50
	s_waitcnt vmcnt(49)
	v_add_f32_e32 v2, v2, v51
	s_waitcnt vmcnt(48)
	v_add_f32_e32 v2, v2, v52
	s_waitcnt vmcnt(47)
	v_add_f32_e32 v2, v2, v53
	s_waitcnt vmcnt(46)
	v_add_f32_e32 v2, v2, v54
	s_waitcnt vmcnt(45)
	v_add_f32_e32 v2, v2, v55
	s_waitcnt vmcnt(44)
	v_add_f32_e32 v2, v2, v56
	s_waitcnt vmcnt(43)
	v_add_f32_e32 v2, v2, v57
	s_waitcnt vmcnt(42)
	v_add_f32_e32 v2, v2, v58
	s_waitcnt vmcnt(41)
	v_add_f32_e32 v2, v2, v59
	s_waitcnt vmcnt(40)
	v_add_f32_e32 v2, v2, v60
	s_waitcnt vmcnt(39)
	v_add_f32_e32 v2, v2, v61
	s_waitcnt vmcnt(38)
	v_add_f32_e32 v2, v2, v62
	s_waitcnt vmcnt(37)
	v_add_f32_e32 v2, v2, v63
	s_waitcnt vmcnt(36)
	v_add_f32_e32 v2, v2, v64
	s_waitcnt vmcnt(35)
	v_add_f32_e32 v2, v2, v65
	s_waitcnt vmcnt(34)
	v_add_f32_e32 v2, v2, v66
	s_waitcnt vmcnt(33)
	v_add_f32_e32 v2, v2, v67
	s_waitcnt vmcnt(32)
	v_add_f32_e32 v2, v2, v68
	s_waitcnt vmcnt(31)
	v_add_f32_e32 v2, v2, v69
	s_waitcnt vmcnt(30)
	v_add_f32_e32 v2, v2, v70
	s_waitcnt vmcnt(29)
	v_add_f32_e32 v2, v2, v71
	s_waitcnt vmcnt(28)
	v_add_f32_e32 v2, v2, v72
	s_waitcnt vmcnt(27)
	v_add_f32_e32 v2, v2, v73
	s_waitcnt vmcnt(26)
	v_add_f32_e32 v2, v2, v74
	s_waitcnt vmcnt(25)
	v_add_f32_e32 v2, v2, v75
	s_waitcnt vmcnt(24)
	v_add_f32_e32 v2, v2, v76
	s_waitcnt vmcnt(23)
	v_add_f32_e32 v2, v2, v77
	s_waitcnt vmcnt(22)
	v_add_f32_e32 v2, v2, v78
	s_waitcnt vmcnt(21)
	v_add_f32_e32 v2, v2, v79
	s_waitcnt vmcnt(20)
	v_add_f32_e32 v2, v2, v80
	s_waitcnt vmcnt(19)
	v_add_f32_e32 v2, v2, v81
	s_waitcnt vmcnt(18)
	v_add_f32_e32 v2, v2, v82
	s_waitcnt vmcnt(17)
	v_add_f32_e32 v2, v2, v83
	s_waitcnt vmcnt(16)
	v_add_f32_e32 v2, v2, v84
	s_waitcnt vmcnt(15)
	v_add_f32_e32 v2, v2, v85
	s_waitcnt vmcnt(14)
	v_add_f32_e32 v2, v2, v86
	s_waitcnt vmcnt(13)
	v_add_f32_e32 v2, v2, v87
	s_waitcnt vmcnt(12)
	v_add_f32_e32 v2, v2, v88
	s_waitcnt vmcnt(11)
	v_add_f32_e32 v2, v2, v89
	s_waitcnt vmcnt(10)
	v_add_f32_e32 v2, v2, v90
	s_waitcnt vmcnt(9)
	v_add_f32_e32 v2, v2, v91
	s_waitcnt vmcnt(8)
	v_add_f32_e32 v2, v2, v92
	s_waitcnt vmcnt(7)
	v_add_f32_e32 v2, v2, v10
	s_waitcnt vmcnt(6)
	v_add_f32_e32 v2, v2, v93
	s_waitcnt vmcnt(5)
	v_add_f32_e32 v2, v2, v94
	s_waitcnt vmcnt(4)
	v_add_f32_e32 v2, v2, v95
	s_waitcnt vmcnt(3)
	v_add_f32_e32 v2, v2, v96
	s_waitcnt vmcnt(2)
	v_add_f32_e32 v2, v2, v97
	s_waitcnt vmcnt(1)
	v_add_f32_e32 v2, v2, v98
	s_waitcnt vmcnt(0)
	v_add_f32_e32 v2, v2, v99
	ds_write_b32 v12, v2
.LBB0_591:
	s_or_b64 exec, exec, s[0:1]
	v_lshl_add_u32 v23, s20, 5, v13
	s_cmpk_gt_u32 s20, 0x7f
	v_lshlrev_b32_e32 v2, 6, v23
	s_cselect_b64 s[12:13], -1, 0
	v_and_or_b32 v24, v2, s17, v17
	v_and_b32_e32 v25, 0xf80, v23
	v_lshl_add_u32 v56, v15, 1, v15
	v_add_u32_e32 v56, v56, v16
	v_add_u32_e32 v56, 0x2000, v56
	s_waitcnt vmcnt(0) lgkmcnt(0)
	s_barrier
	ds_read_b128 v[42:45], v14
	s_waitcnt lgkmcnt(0)
	v_pk_add_f32 v[26:27], v[42:43], v[100:101]
	v_pk_add_f32 v[28:29], v[44:45], v[102:103]
	v_pk_add_f32 v[30:31], v[42:43], v[116:117]
	v_pk_add_f32 v[32:33], v[44:45], v[118:119]
	v_pk_add_f32 v[34:35], v[42:43], v[132:133]
	v_pk_add_f32 v[36:37], v[44:45], v[134:135]
	v_pk_add_f32 v[38:39], v[42:43], v[152:153]
	v_pk_add_f32 v[40:41], v[44:45], v[154:155]
	v_pk_add_f32 v[26:27], v[26:27], v[104:105]
	v_pk_add_f32 v[28:29], v[28:29], v[106:107]
	v_pk_add_f32 v[30:31], v[30:31], v[120:121]
	v_pk_add_f32 v[32:33], v[32:33], v[122:123]
	v_pk_add_f32 v[34:35], v[34:35], v[136:137]
	v_pk_add_f32 v[36:37], v[36:37], v[138:139]
	v_pk_add_f32 v[38:39], v[38:39], v[156:157]
	v_pk_add_f32 v[40:41], v[40:41], v[158:159]
	v_pk_add_f32 v[26:27], v[26:27], v[108:109]
	v_pk_add_f32 v[28:29], v[28:29], v[110:111]
	v_pk_add_f32 v[30:31], v[30:31], v[124:125]
	v_pk_add_f32 v[32:33], v[32:33], v[126:127]
	v_pk_add_f32 v[34:35], v[34:35], v[140:141]
	v_pk_add_f32 v[36:37], v[36:37], v[142:143]
	v_pk_add_f32 v[38:39], v[38:39], v[160:161]
	v_pk_add_f32 v[40:41], v[40:41], v[162:163]
	v_pk_add_f32 v[26:27], v[26:27], v[112:113]
	v_pk_add_f32 v[28:29], v[28:29], v[114:115]
	v_pk_add_f32 v[30:31], v[30:31], v[128:129]
	v_pk_add_f32 v[32:33], v[32:33], v[130:131]
	v_pk_add_f32 v[34:35], v[34:35], v[144:145]
	v_pk_add_f32 v[36:37], v[36:37], v[146:147]
	v_pk_add_f32 v[38:39], v[38:39], v[164:165]
	v_pk_add_f32 v[40:41], v[40:41], v[166:167]
	v_mov_b32_e32 v62, 0xc0135761
	s_mov_b32 s0, 0xbdd2d3e8
	v_mul_f32_e32 v64, v26, v26
	v_mul_f32_e32 v65, v27, v27
	v_mul_f32_e32 v66, v28, v28
	v_mul_f32_e32 v67, v29, v29
	v_mul_f32_e32 v68, v30, v30
	v_mul_f32_e32 v69, v31, v31
	v_mul_f32_e32 v70, v32, v32
	v_mul_f32_e32 v71, v33, v33
	v_mul_f32_e32 v72, v34, v34
	v_mul_f32_e32 v73, v35, v35
	v_mul_f32_e32 v74, v36, v36
	v_mul_f32_e32 v75, v37, v37
	v_mul_f32_e32 v76, v38, v38
	v_mul_f32_e32 v77, v39, v39
	v_mul_f32_e32 v78, v40, v40
	v_mul_f32_e32 v79, v41, v41
	v_fma_f32 v64, v64, s0, v62
	v_fma_f32 v65, v65, s0, v62
	v_fma_f32 v66, v66, s0, v62
	v_fma_f32 v67, v67, s0, v62
	v_fma_f32 v68, v68, s0, v62
	v_fma_f32 v69, v69, s0, v62
	v_fma_f32 v70, v70, s0, v62
	v_fma_f32 v71, v71, s0, v62
; #define LAS __attribute__((address_space(3)))
; __device__ __forceinline__ void phase3(const Args& a, LAS unsigned char* lds) {
;     ...
;             f32x4 h4 = *(const LAS f32x4*)(c1s + 4 * lane);
; #pragma unroll
;             for (int kc = 0; kc < 4; ++kc) h4 += *(const f32x4*)(part + ((size_t)kc * 8192 + R) * 256 + 4 * lane);
;             h4.x = gelu_tanh(h4.x); h4.y = gelu_tanh(h4.y); h4.z = gelu_tanh(h4.z); h4.w = gelu_tanh(h4.w);
;             *(LAS f32x4*)(hids + wave * 256 + 4 * lane) = h4;
;             asm volatile("s_waitcnt lgkmcnt(0)" ::: "memory");
;             float acc = 0.f;
; #pragma unroll 8
;             for (int c = 0; c < 256; ++c) acc += hids[wave * 256 + c] * w2s[c * 64 + lane];
	v_fma_f32 v72, v72, s0, v62
	v_fma_f32 v73, v73, s0, v62
	v_fma_f32 v74, v74, s0, v62
	v_fma_f32 v75, v75, s0, v62
	v_fma_f32 v76, v76, s0, v62
	v_fma_f32 v77, v77, s0, v62
	v_fma_f32 v78, v78, s0, v62
	v_fma_f32 v79, v79, s0, v62
	v_mul_f32_e32 v64, v26, v64
	v_mul_f32_e32 v65, v27, v65
	v_mul_f32_e32 v66, v28, v66
	v_mul_f32_e32 v67, v29, v67
	v_mul_f32_e32 v68, v30, v68
	v_mul_f32_e32 v69, v31, v69
	v_mul_f32_e32 v70, v32, v70
	v_mul_f32_e32 v71, v33, v71
	v_mul_f32_e32 v72, v34, v72
	v_mul_f32_e32 v73, v35, v73
	v_mul_f32_e32 v74, v36, v74
	v_mul_f32_e32 v75, v37, v75
	v_mul_f32_e32 v76, v38, v76
	v_mul_f32_e32 v77, v39, v77
	v_mul_f32_e32 v78, v40, v78
	v_mul_f32_e32 v79, v41, v79
	v_exp_f32_e32 v64, v64
	v_exp_f32_e32 v65, v65
	v_exp_f32_e32 v66, v66
	v_exp_f32_e32 v67, v67
	v_exp_f32_e32 v68, v68
	v_exp_f32_e32 v69, v69
	v_exp_f32_e32 v70, v70
	v_exp_f32_e32 v71, v71
	v_exp_f32_e32 v72, v72
	v_exp_f32_e32 v73, v73
	v_exp_f32_e32 v74, v74
	v_exp_f32_e32 v75, v75
	v_exp_f32_e32 v76, v76
	v_exp_f32_e32 v77, v77
	v_exp_f32_e32 v78, v78
	v_exp_f32_e32 v79, v79
	v_add_f32_e32 v64, 1.0, v64
	v_add_f32_e32 v65, 1.0, v65
	v_add_f32_e32 v66, 1.0, v66
	v_add_f32_e32 v67, 1.0, v67
	v_add_f32_e32 v68, 1.0, v68
	v_add_f32_e32 v69, 1.0, v69
	v_add_f32_e32 v70, 1.0, v70
	v_add_f32_e32 v71, 1.0, v71
	v_add_f32_e32 v72, 1.0, v72
	v_add_f32_e32 v73, 1.0, v73
	v_add_f32_e32 v74, 1.0, v74
	v_add_f32_e32 v75, 1.0, v75
	v_add_f32_e32 v76, 1.0, v76
	v_add_f32_e32 v77, 1.0, v77
	v_add_f32_e32 v78, 1.0, v78
	v_add_f32_e32 v79, 1.0, v79
	v_rcp_f32_e32 v64, v64
	v_rcp_f32_e32 v65, v65
	v_rcp_f32_e32 v66, v66
	v_rcp_f32_e32 v67, v67
	v_rcp_f32_e32 v68, v68
	v_rcp_f32_e32 v69, v69
	v_rcp_f32_e32 v70, v70
	v_rcp_f32_e32 v71, v71
	v_rcp_f32_e32 v72, v72
	v_rcp_f32_e32 v73, v73
	v_rcp_f32_e32 v74, v74
	v_rcp_f32_e32 v75, v75
	v_rcp_f32_e32 v76, v76
	v_rcp_f32_e32 v77, v77
	v_rcp_f32_e32 v78, v78
	v_rcp_f32_e32 v79, v79
	v_mul_f32_e32 v26, v26, v64
	v_mul_f32_e32 v27, v27, v65
	v_mul_f32_e32 v28, v28, v66
	v_mul_f32_e32 v29, v29, v67
	v_mul_f32_e32 v30, v30, v68
	v_mul_f32_e32 v31, v31, v69
	v_mul_f32_e32 v32, v32, v70
	v_mul_f32_e32 v33, v33, v71
	v_mul_f32_e32 v34, v34, v72
	v_mul_f32_e32 v35, v35, v73
	v_mul_f32_e32 v36, v36, v74
	v_mul_f32_e32 v37, v37, v75
	v_mul_f32_e32 v38, v38, v76
	v_mul_f32_e32 v39, v39, v77
	v_mul_f32_e32 v40, v40, v78
	v_mul_f32_e32 v41, v41, v79
	ds_write_b128 v56, v[26:29]
	ds_write_b128 v56, v[30:33] offset:1024
	ds_write_b128 v56, v[34:37] offset:2048
	ds_write_b128 v56, v[38:41] offset:3072
	v_and_b32_e32 v168, 15, v22
	v_lshrrev_b32_e32 v169, 4, v22
	v_and_b32_e32 v170, 1, v149
	v_lshrrev_b32_e32 v171, 1, v149
	v_lshlrev_b32_e32 v172, 14, v170
	v_lshl_add_u32 v172, v168, 10, v172
	v_lshl_add_u32 v172, v171, 8, v172
	v_lshl_add_u32 v172, v169, 6, v172
	v_add_u32_e32 v172, 0x12400, v172
	v_lshlrev_b32_e32 v173, 14, v171
	v_lshl_add_u32 v173, v169, 12, v173
	v_lshl_add_u32 v173, v168, 2, v173
	v_lshlrev_b32_e32 v174, 2, v170
	v_add_u32_e32 v174, v174, v169
	v_mul_u32_u24_e32 v174, 0x440, v174
	v_mul_u32_u24_e32 v175, 0x2200, v171
	v_add_u32_e32 v174, v174, v175
	v_add_u32_e32 v174, 0x1a400, v174
	v_lshl_add_u32 v174, v168, 2, v174
	v_mul_u32_u24_e32 v175, 0x440, v149
	v_add_u32_e32 v175, 0x1a400, v175
	v_lshl_add_u32 v175, v22, 2, v175
	s_waitcnt lgkmcnt(0)
	s_barrier
	ds_read_b128 v[64:67], v172 offset:0
	ds_read_b128 v[68:71], v172 offset:16
	ds_read_b128 v[72:75], v172 offset:32
	ds_read_b128 v[76:79], v172 offset:48
	v_add_u32_e32 v181, 64, v173
	v_add_u32_e32 v182, 128, v173
	v_add_u32_e32 v183, 192, v173
	ds_read2st64_b32 v[80:81], v173 offset0:0 offset1:1
	ds_read2st64_b32 v[96:97], v181 offset0:0 offset1:1
	ds_read2st64_b32 v[112:113], v182 offset0:0 offset1:1
	ds_read2st64_b32 v[128:129], v183 offset0:0 offset1:1
	ds_read2st64_b32 v[82:83], v173 offset0:2 offset1:3
	ds_read2st64_b32 v[98:99], v181 offset0:2 offset1:3
	ds_read2st64_b32 v[114:115], v182 offset0:2 offset1:3
	ds_read2st64_b32 v[130:131], v183 offset0:2 offset1:3
	ds_read2st64_b32 v[84:85], v173 offset0:4 offset1:5
	ds_read2st64_b32 v[100:101], v181 offset0:4 offset1:5
	ds_read2st64_b32 v[116:117], v182 offset0:4 offset1:5
	ds_read2st64_b32 v[132:133], v183 offset0:4 offset1:5
	ds_read2st64_b32 v[86:87], v173 offset0:6 offset1:7
	ds_read2st64_b32 v[102:103], v181 offset0:6 offset1:7
	ds_read2st64_b32 v[118:119], v182 offset0:6 offset1:7
	ds_read2st64_b32 v[134:135], v183 offset0:6 offset1:7
	ds_read2st64_b32 v[88:89], v173 offset0:8 offset1:9
	ds_read2st64_b32 v[104:105], v181 offset0:8 offset1:9
	ds_read2st64_b32 v[120:121], v182 offset0:8 offset1:9
	ds_read2st64_b32 v[136:137], v183 offset0:8 offset1:9
	ds_read2st64_b32 v[90:91], v173 offset0:10 offset1:11
	ds_read2st64_b32 v[106:107], v181 offset0:10 offset1:11
	ds_read2st64_b32 v[122:123], v182 offset0:10 offset1:11
	ds_read2st64_b32 v[138:139], v183 offset0:10 offset1:11
	ds_read2st64_b32 v[92:93], v173 offset0:12 offset1:13
	ds_read2st64_b32 v[108:109], v181 offset0:12 offset1:13
	ds_read2st64_b32 v[124:125], v182 offset0:12 offset1:13
	ds_read2st64_b32 v[140:141], v183 offset0:12 offset1:13
	ds_read2st64_b32 v[94:95], v173 offset0:14 offset1:15
	ds_read2st64_b32 v[110:111], v181 offset0:14 offset1:15
	ds_read2st64_b32 v[126:127], v182 offset0:14 offset1:15
	ds_read2st64_b32 v[142:143], v183 offset0:14 offset1:15
	s_waitcnt lgkmcnt(15)
; __device__ __forceinline__ unsigned f2bf(float f) { unsigned u = __float_as_uint(f); return (u + 0x7fffu + ((u >> 16) & 1u)) >> 16; }
; __device__ __forceinline__ void phase3(const Args& a, LAS unsigned char* lds) {
;     ...
;             float acc = 0.f;
; #pragma unroll 8
;             for (int c = 0; c < 256; ++c) acc += hids[wave * 256 + c] * w2s[c * 64 + lane];
;             if (kv == 0) {
;                 const float ss = wave_sum(acc * acc);
;                 const float y = acc * rsqrtf(ss * (1.f / 64.f) + EPS) * a.in[4][lane];
;                 kcmp[((size_t)bh * 128 + n) * 64 + lane] = (bf16_t)f2bf(n < 127 ? y : 0.f);
;             } else {
;                 vcmpT[((size_t)bh * 64 + lane) * 128 + n] = (bf16_t)f2bf(n < 127 ? acc : 0.f);
	v_mfma_f32_16x16x4_f32 v[152:155], v64, v80, 0
	v_mfma_f32_16x16x4_f32 v[156:159], v64, v96, 0
	v_mfma_f32_16x16x4_f32 v[160:163], v64, v112, 0
	v_mfma_f32_16x16x4_f32 v[164:167], v64, v128, 0
	v_mfma_f32_16x16x4_f32 v[152:155], v65, v81, v[152:155]
	v_mfma_f32_16x16x4_f32 v[156:159], v65, v97, v[156:159]
	v_mfma_f32_16x16x4_f32 v[160:163], v65, v113, v[160:163]
	v_mfma_f32_16x16x4_f32 v[164:167], v65, v129, v[164:167]
	v_mfma_f32_16x16x4_f32 v[152:155], v66, v82, v[152:155]
	v_mfma_f32_16x16x4_f32 v[156:159], v66, v98, v[156:159]
	v_mfma_f32_16x16x4_f32 v[160:163], v66, v114, v[160:163]
	v_mfma_f32_16x16x4_f32 v[164:167], v66, v130, v[164:167]
	v_mfma_f32_16x16x4_f32 v[152:155], v67, v83, v[152:155]
	v_mfma_f32_16x16x4_f32 v[156:159], v67, v99, v[156:159]
	v_mfma_f32_16x16x4_f32 v[160:163], v67, v115, v[160:163]
	v_mfma_f32_16x16x4_f32 v[164:167], v67, v131, v[164:167]
	v_mfma_f32_16x16x4_f32 v[152:155], v68, v84, v[152:155]
	v_mfma_f32_16x16x4_f32 v[156:159], v68, v100, v[156:159]
	v_mfma_f32_16x16x4_f32 v[160:163], v68, v116, v[160:163]
	v_mfma_f32_16x16x4_f32 v[164:167], v68, v132, v[164:167]
	v_mfma_f32_16x16x4_f32 v[152:155], v69, v85, v[152:155]
	v_mfma_f32_16x16x4_f32 v[156:159], v69, v101, v[156:159]
	v_mfma_f32_16x16x4_f32 v[160:163], v69, v117, v[160:163]
	v_mfma_f32_16x16x4_f32 v[164:167], v69, v133, v[164:167]
	v_mfma_f32_16x16x4_f32 v[152:155], v70, v86, v[152:155]
	v_mfma_f32_16x16x4_f32 v[156:159], v70, v102, v[156:159]
	v_mfma_f32_16x16x4_f32 v[160:163], v70, v118, v[160:163]
	v_mfma_f32_16x16x4_f32 v[164:167], v70, v134, v[164:167]
	v_mfma_f32_16x16x4_f32 v[152:155], v71, v87, v[152:155]
	v_mfma_f32_16x16x4_f32 v[156:159], v71, v103, v[156:159]
	v_mfma_f32_16x16x4_f32 v[160:163], v71, v119, v[160:163]
	v_mfma_f32_16x16x4_f32 v[164:167], v71, v135, v[164:167]
	v_mfma_f32_16x16x4_f32 v[152:155], v72, v88, v[152:155]
	s_waitcnt lgkmcnt(14)
	v_mfma_f32_16x16x4_f32 v[156:159], v72, v104, v[156:159]
	s_waitcnt lgkmcnt(13)
	v_mfma_f32_16x16x4_f32 v[160:163], v72, v120, v[160:163]
	s_waitcnt lgkmcnt(12)
	v_mfma_f32_16x16x4_f32 v[164:167], v72, v136, v[164:167]
	v_mfma_f32_16x16x4_f32 v[152:155], v73, v89, v[152:155]
	v_mfma_f32_16x16x4_f32 v[156:159], v73, v105, v[156:159]
	v_mfma_f32_16x16x4_f32 v[160:163], v73, v121, v[160:163]
	v_mfma_f32_16x16x4_f32 v[164:167], v73, v137, v[164:167]
	s_waitcnt lgkmcnt(11)
	v_mfma_f32_16x16x4_f32 v[152:155], v74, v90, v[152:155]
	s_waitcnt lgkmcnt(10)
	v_mfma_f32_16x16x4_f32 v[156:159], v74, v106, v[156:159]
	s_waitcnt lgkmcnt(9)
	v_mfma_f32_16x16x4_f32 v[160:163], v74, v122, v[160:163]
	s_waitcnt lgkmcnt(8)
	v_mfma_f32_16x16x4_f32 v[164:167], v74, v138, v[164:167]
	v_mfma_f32_16x16x4_f32 v[152:155], v75, v91, v[152:155]
	v_mfma_f32_16x16x4_f32 v[156:159], v75, v107, v[156:159]
	v_mfma_f32_16x16x4_f32 v[160:163], v75, v123, v[160:163]
	v_mfma_f32_16x16x4_f32 v[164:167], v75, v139, v[164:167]
	s_waitcnt lgkmcnt(7)
	v_mfma_f32_16x16x4_f32 v[152:155], v76, v92, v[152:155]
	s_waitcnt lgkmcnt(6)
	v_mfma_f32_16x16x4_f32 v[156:159], v76, v108, v[156:159]
	s_waitcnt lgkmcnt(5)
	v_mfma_f32_16x16x4_f32 v[160:163], v76, v124, v[160:163]
	s_waitcnt lgkmcnt(4)
	v_mfma_f32_16x16x4_f32 v[164:167], v76, v140, v[164:167]
	v_mfma_f32_16x16x4_f32 v[152:155], v77, v93, v[152:155]
	v_mfma_f32_16x16x4_f32 v[156:159], v77, v109, v[156:159]
	v_mfma_f32_16x16x4_f32 v[160:163], v77, v125, v[160:163]
	v_mfma_f32_16x16x4_f32 v[164:167], v77, v141, v[164:167]
	s_waitcnt lgkmcnt(3)
	v_mfma_f32_16x16x4_f32 v[152:155], v78, v94, v[152:155]
	s_waitcnt lgkmcnt(2)
	v_mfma_f32_16x16x4_f32 v[156:159], v78, v110, v[156:159]
	s_waitcnt lgkmcnt(1)
	v_mfma_f32_16x16x4_f32 v[160:163], v78, v126, v[160:163]
	s_waitcnt lgkmcnt(0)
	v_mfma_f32_16x16x4_f32 v[164:167], v78, v142, v[164:167]
	v_mfma_f32_16x16x4_f32 v[152:155], v79, v95, v[152:155]
	v_mfma_f32_16x16x4_f32 v[156:159], v79, v111, v[156:159]
	v_mfma_f32_16x16x4_f32 v[160:163], v79, v127, v[160:163]
	v_mfma_f32_16x16x4_f32 v[164:167], v79, v143, v[164:167]
	s_nop 7
	s_nop 7
	ds_write_b32 v174, v152 offset:0
	ds_write_b32 v174, v153 offset:272
	ds_write_b32 v174, v154 offset:544
	ds_write_b32 v174, v155 offset:816
	ds_write_b32 v174, v156 offset:64
	ds_write_b32 v174, v157 offset:336
	ds_write_b32 v174, v158 offset:608
	ds_write_b32 v174, v159 offset:880
	ds_write_b32 v174, v160 offset:128
	ds_write_b32 v174, v161 offset:400
	ds_write_b32 v174, v162 offset:672
	ds_write_b32 v174, v163 offset:944
	ds_write_b32 v174, v164 offset:192
	ds_write_b32 v174, v165 offset:464
	ds_write_b32 v174, v166 offset:736
	ds_write_b32 v174, v167 offset:1008
	s_waitcnt lgkmcnt(0)
	s_barrier
	ds_read_b32 v64, v175 offset:0
	ds_read_b32 v65, v175 offset:8704
	ds_read_b32 v66, v175 offset:17408
	ds_read_b32 v67, v175 offset:26112
	ds_read_b32 v68, v175 offset:272
	ds_read_b32 v69, v175 offset:8976
	ds_read_b32 v70, v175 offset:17680
	ds_read_b32 v71, v175 offset:26384
	ds_read_b32 v72, v175 offset:544
	ds_read_b32 v73, v175 offset:9248
	ds_read_b32 v74, v175 offset:17952
	ds_read_b32 v75, v175 offset:26656
	ds_read_b32 v76, v175 offset:816
	ds_read_b32 v77, v175 offset:9520
	ds_read_b32 v78, v175 offset:18224
	ds_read_b32 v79, v175 offset:26928
	v_mov_b32_e32 v177, v23
	v_or_b32_e32 v178, 1, v23
	v_or_b32_e32 v179, 2, v23
	v_or_b32_e32 v180, 3, v23
	v_and_b32_e32 v177, 0x7f, v177
	v_and_b32_e32 v178, 0x7f, v178
	v_and_b32_e32 v179, 0x7f, v179
	v_and_b32_e32 v180, 0x7f, v180
	s_waitcnt lgkmcnt(0)
	v_add_f32_e32 v60, v64, v65
	v_add_f32_e32 v61, v68, v69
	v_add_f32_e32 v62, v72, v73
	v_add_f32_e32 v63, v76, v77
	v_add_f32_e32 v60, v60, v66
	v_add_f32_e32 v61, v61, v70
	v_add_f32_e32 v62, v62, v74
	v_add_f32_e32 v63, v63, v78
	v_add_f32_e32 v60, v60, v67
	v_add_f32_e32 v61, v61, v71
	v_add_f32_e32 v62, v62, v75
	v_add_f32_e32 v63, v63, v79
	s_and_b64 vcc, exec, s[12:13]
	s_cbranch_vccz .Lp3_kpath
	v_cmp_ne_u32_e64 s[4:5], s16, v177
	v_cmp_ne_u32_e64 s[6:7], s16, v178
	v_cmp_ne_u32_e64 s[28:29], s16, v179
	v_cmp_ne_u32_e64 s[30:31], s16, v180
	s_mov_b64 s[0:1], 0x2180000
	s_add_u32 s0, s78, s0
	s_addc_u32 s1, s79, s1
	v_cndmask_b32_e64 v64, 0, v60, s[4:5]
	v_cndmask_b32_e64 v65, 0, v61, s[6:7]
	v_cndmask_b32_e64 v66, 0, v62, s[28:29]
	v_cndmask_b32_e64 v67, 0, v63, s[30:31]
	v_bfe_u32 v68, v64, 16, 1
	v_bfe_u32 v69, v65, 16, 1
	v_bfe_u32 v70, v66, 16, 1
	v_bfe_u32 v71, v67, 16, 1
	v_add3_u32 v64, v64, v68, s19
	v_add3_u32 v65, v65, v69, s19
	v_add3_u32 v66, v66, v70, s19
	v_add3_u32 v67, v67, v71, s19
	v_or_b32_e32 v72, v177, v24
	v_mov_b32_e32 v73, 0
	v_or_b32_e32 v74, v178, v24
	v_mov_b32_e32 v75, 0
	v_or_b32_e32 v76, v179, v24
	v_mov_b32_e32 v77, 0
	v_or_b32_e32 v78, v180, v24
	v_mov_b32_e32 v79, 0
	v_lshl_add_u64 v[72:73], v[72:73], 1, s[0:1]
	v_lshl_add_u64 v[74:75], v[74:75], 1, s[0:1]
	v_lshl_add_u64 v[76:77], v[76:77], 1, s[0:1]
	v_lshl_add_u64 v[78:79], v[78:79], 1, s[0:1]
	global_store_short_d16_hi v[72:73], v64, off
	global_store_short_d16_hi v[74:75], v65, off
	global_store_short_d16_hi v[76:77], v66, off
	global_store_short_d16_hi v[78:79], v67, off
	s_branch .LBB0_588
; __device__ __forceinline__ unsigned f2bf(float f) { unsigned u = __float_as_uint(f); return (u + 0x7fffu + ((u >> 16) & 1u)) >> 16; }
; __device__ __forceinline__ void phase3(const Args& a, LAS unsigned char* lds) {
;     ...
;             if (kv == 0) {
;                 const float ss = wave_sum(acc * acc);
;                 const float y = acc * rsqrtf(ss * (1.f / 64.f) + EPS) * a.in[4][lane];
;                 kcmp[((size_t)bh * 128 + n) * 64 + lane] = (bf16_t)f2bf(n < 127 ? y : 0.f);
.Lp3_kpath:
	v_lshlrev_b32_e32 v181, 2, v22
	v_mul_f32_e32 v64, v60, v60
	v_mul_f32_e32 v65, v61, v61
	v_mul_f32_e32 v66, v62, v62
	v_mul_f32_e32 v67, v63, v63
	v_xor_b32_e32 v182, 4, v181
	ds_bpermute_b32 v68, v182, v64
	ds_bpermute_b32 v69, v182, v65
	ds_bpermute_b32 v70, v182, v66
	ds_bpermute_b32 v71, v182, v67
	s_waitcnt lgkmcnt(0)
	v_fma_f32 v64, v60, v60, v68
	v_fma_f32 v65, v61, v61, v69
	v_fma_f32 v66, v62, v62, v70
	v_fma_f32 v67, v63, v63, v71
	v_xor_b32_e32 v182, 8, v181
	ds_bpermute_b32 v68, v182, v64
	ds_bpermute_b32 v69, v182, v65
	ds_bpermute_b32 v70, v182, v66
	ds_bpermute_b32 v71, v182, v67
	s_waitcnt lgkmcnt(0)
	v_add_f32_e32 v64, v64, v68
	v_add_f32_e32 v65, v65, v69
	v_add_f32_e32 v66, v66, v70
	v_add_f32_e32 v67, v67, v71
	v_xor_b32_e32 v182, 16, v181
	ds_bpermute_b32 v68, v182, v64
	ds_bpermute_b32 v69, v182, v65
	ds_bpermute_b32 v70, v182, v66
	ds_bpermute_b32 v71, v182, v67
	s_waitcnt lgkmcnt(0)
	v_add_f32_e32 v64, v64, v68
	v_add_f32_e32 v65, v65, v69
	v_add_f32_e32 v66, v66, v70
	v_add_f32_e32 v67, v67, v71
	v_xor_b32_e32 v182, 32, v181
	ds_bpermute_b32 v68, v182, v64
	ds_bpermute_b32 v69, v182, v65
	ds_bpermute_b32 v70, v182, v66
	ds_bpermute_b32 v71, v182, v67
	s_waitcnt lgkmcnt(0)
	v_add_f32_e32 v64, v64, v68
	v_add_f32_e32 v65, v65, v69
	v_add_f32_e32 v66, v66, v70
	v_add_f32_e32 v67, v67, v71
	v_xor_b32_e32 v182, 64, v181
	ds_bpermute_b32 v68, v182, v64
	ds_bpermute_b32 v69, v182, v65
	ds_bpermute_b32 v70, v182, v66
	ds_bpermute_b32 v71, v182, v67
	s_waitcnt lgkmcnt(0)
	v_add_f32_e32 v64, v64, v68
	v_add_f32_e32 v65, v65, v69
	v_add_f32_e32 v66, v66, v70
	v_add_f32_e32 v67, v67, v71
	v_xor_b32_e32 v182, 128, v181
	ds_bpermute_b32 v68, v182, v64
	ds_bpermute_b32 v69, v182, v65
	ds_bpermute_b32 v70, v182, v66
	ds_bpermute_b32 v71, v182, v67
	s_waitcnt lgkmcnt(0)
	v_add_f32_e32 v64, v64, v68
	v_add_f32_e32 v65, v65, v69
	v_add_f32_e32 v66, v66, v70
	v_add_f32_e32 v67, v67, v71
	v_fmamk_f32 v64, v64, 0x3c800000, v21
	v_fmamk_f32 v65, v65, 0x3c800000, v21
	v_fmamk_f32 v66, v66, 0x3c800000, v21
	v_fmamk_f32 v67, v67, 0x3c800000, v21
	v_cmp_gt_f32_e64 s[4:5], s18, v64
	v_cmp_gt_f32_e64 s[6:7], s18, v65
	v_cmp_gt_f32_e64 s[28:29], s18, v66
	v_cmp_gt_f32_e64 s[30:31], s18, v67
	v_mul_f32_e32 v68, 0x4b800000, v64
	v_mul_f32_e32 v69, 0x4b800000, v65
	v_mul_f32_e32 v70, 0x4b800000, v66
	v_mul_f32_e32 v71, 0x4b800000, v67
	v_cndmask_b32_e64 v64, v64, v68, s[4:5]
	v_cndmask_b32_e64 v65, v65, v69, s[6:7]
	v_cndmask_b32_e64 v66, v66, v70, s[28:29]
	v_cndmask_b32_e64 v67, v67, v71, s[30:31]
	v_rsq_f32_e32 v64, v64
	v_rsq_f32_e32 v65, v65
	v_rsq_f32_e32 v66, v66
	v_rsq_f32_e32 v67, v67
	s_mov_b64 s[0:1], 0x2100000
	s_add_u32 s0, s78, s0
	s_addc_u32 s1, s79, s1
	v_mul_f32_e32 v68, 0x45800000, v64
	v_mul_f32_e32 v69, 0x45800000, v65
	v_mul_f32_e32 v70, 0x45800000, v66
	v_mul_f32_e32 v71, 0x45800000, v67
	v_cndmask_b32_e64 v64, v64, v68, s[4:5]
	v_cndmask_b32_e64 v65, v65, v69, s[6:7]
	v_cndmask_b32_e64 v66, v66, v70, s[28:29]
	v_cndmask_b32_e64 v67, v67, v71, s[30:31]
	v_mul_f32_e32 v64, v60, v64
	v_mul_f32_e32 v65, v61, v65
	v_mul_f32_e32 v66, v62, v66
	v_mul_f32_e32 v67, v63, v67
	v_cmp_ne_u32_e64 s[4:5], s16, v177
	v_cmp_ne_u32_e64 s[6:7], s16, v178
	v_cmp_ne_u32_e64 s[28:29], s16, v179
	v_cmp_ne_u32_e64 s[30:31], s16, v180
	v_mul_f32_e32 v64, v176, v64
	v_mul_f32_e32 v65, v176, v65
	v_mul_f32_e32 v66, v176, v66
	v_mul_f32_e32 v67, v176, v67
	v_cndmask_b32_e64 v64, 0, v64, s[4:5]
	v_cndmask_b32_e64 v65, 0, v65, s[6:7]
	v_cndmask_b32_e64 v66, 0, v66, s[28:29]
	v_cndmask_b32_e64 v67, 0, v67, s[30:31]
	v_bfe_u32 v68, v64, 16, 1
	v_bfe_u32 v69, v65, 16, 1
	v_bfe_u32 v70, v66, 16, 1
	v_bfe_u32 v71, v67, 16, 1
	v_add3_u32 v64, v64, v68, s19
	v_add3_u32 v65, v65, v69, s19
	v_add3_u32 v66, v66, v70, s19
	v_add3_u32 v67, v67, v71, s19
	v_or_b32_e32 v72, v177, v25
	v_mov_b32_e32 v73, 0
	v_or_b32_e32 v74, v178, v25
	v_mov_b32_e32 v75, 0
	v_or_b32_e32 v76, v179, v25
	v_mov_b32_e32 v77, 0
	v_or_b32_e32 v78, v180, v25
	v_mov_b32_e32 v79, 0
	v_lshl_or_b32 v72, v72, 6, v151
	v_lshl_or_b32 v74, v74, 6, v151
	v_lshl_or_b32 v76, v76, 6, v151
	v_lshl_or_b32 v78, v78, 6, v151
	v_lshl_add_u64 v[72:73], v[72:73], 1, s[0:1]
	v_lshl_add_u64 v[74:75], v[74:75], 1, s[0:1]
	v_lshl_add_u64 v[76:77], v[76:77], 1, s[0:1]
	v_lshl_add_u64 v[78:79], v[78:79], 1, s[0:1]
	global_store_short_d16_hi v[72:73], v64, off
	global_store_short_d16_hi v[74:75], v65, off
	global_store_short_d16_hi v[76:77], v66, off
	global_store_short_d16_hi v[78:79], v67, off
	s_branch .LBB0_588
